# v44
# baseline (speedup 1.0000x reference)
.LBB0_476:
	s_cmpk_eq_i32 s26, 0x7f0
	s_cbranch_scc1 .LBB0_499
	s_setprio 2
	v_mov_b32_e32 v44, 1.0
	s_and_saveexec_b64 s[12:13], s[10:11]
	s_cbranch_execz .LBB0_479
	v_and_b32_e32 v33, 0xffff0000, v157
	v_lshlrev_b32_e32 v32, 16, v157
	v_pk_add_f32 v[32:33], v[32:33], 1.0 op_sel_hi:[1,0] neg_lo:[1,0] neg_hi:[1,0]
	v_and_b32_e32 v35, 0xffff0000, v156
	v_lshlrev_b32_e32 v34, 16, v156
	v_pk_add_f32 v[34:35], v[34:35], 1.0 op_sel_hi:[1,0] neg_lo:[1,0] neg_hi:[1,0]
	v_mul_f32_e32 v32, v32, v33
	v_and_b32_e32 v37, 0xffff0000, v155
	v_lshlrev_b32_e32 v36, 16, v155
	v_mul_f32_e32 v32, v35, v32
	v_pk_add_f32 v[36:37], v[36:37], 1.0 op_sel_hi:[1,0] neg_lo:[1,0] neg_hi:[1,0]
	v_mul_f32_e32 v32, v34, v32
	v_and_b32_e32 v39, 0xffff0000, v154
	v_lshlrev_b32_e32 v38, 16, v154
	v_mul_f32_e32 v32, v37, v32
	v_pk_add_f32 v[38:39], v[38:39], 1.0 op_sel_hi:[1,0] neg_lo:[1,0] neg_hi:[1,0]
	v_mul_f32_e32 v32, v36, v32
	v_mul_f32_e32 v32, v39, v32
	v_mul_f32_e32 v44, v38, v32

.LBB0_499:
	s_setprio 0
	s_andn2_saveexec_b64 s[12:13], s[28:29]
	s_cbranch_execz .LBB0_534
	s_cmp_eq_u32 s26, -16
	s_cbranch_scc1 .LBB0_534
	s_bitcmp1_b32 s34, 0
	s_cselect_b32 s28, 0x5180, 0
	v_add_u32_e32 v50, s28, v72
	v_lshl_add_u32 v59, v74, 2, v50
	s_waitcnt lgkmcnt(0)
	ds_read_b128 v[34:37], v59
	ds_read_b128 v[38:41], v59 offset:32
	ds_read_b128 v[42:45], v59 offset:768
	ds_read_b128 v[162:165], v59 offset:800
	ds_read_b128 v[166:169], v59 offset:64
	ds_read_b128 v[170:173], v59 offset:96
	ds_read_b128 v[174:177], v59 offset:832
	ds_read_b128 v[178:181], v59 offset:864
	ds_read_b128 v[182:185], v59 offset:128
	ds_read_b128 v[186:189], v59 offset:160
	ds_read_b128 v[190:193], v59 offset:192
	ds_read_b128 v[194:197], v59 offset:224
	s_waitcnt lgkmcnt(11)
	v_pk_fma_f32 v[36:37], v[2:3], v[36:37], 0 op_sel_hi:[1,1,0]
	v_pk_fma_f32 v[34:35], v[0:1], v[34:35], 0 op_sel_hi:[1,1,0]
	s_waitcnt lgkmcnt(3)
	v_pk_fma_f32 v[46:47], v[18:19], v[184:185], 0 op_sel_hi:[1,1,0]
	v_pk_fma_f32 v[182:183], v[16:17], v[182:183], 0 op_sel_hi:[1,1,0]
	v_pk_fma_f32 v[36:37], v[6:7], v[40:41], v[36:37]
	v_pk_fma_f32 v[34:35], v[4:5], v[38:39], v[34:35]
	s_waitcnt lgkmcnt(2)
	v_pk_fma_f32 v[38:39], v[22:23], v[188:189], v[46:47]
	v_lshl_add_u32 v61, v102, 2, v50
	v_pk_fma_f32 v[40:41], v[20:21], v[186:187], v[182:183]
	v_pk_fma_f32 v[36:37], v[10:11], v[168:169], v[36:37]
	v_pk_fma_f32 v[34:35], v[8:9], v[166:167], v[34:35]
	s_waitcnt lgkmcnt(1)
	v_pk_fma_f32 v[38:39], v[26:27], v[192:193], v[38:39]
	ds_read2_b32 v[198:199], v61 offset0:64 offset1:96
	v_pk_fma_f32 v[40:41], v[24:25], v[190:191], v[40:41]
	v_pk_fma_f32 v[36:37], v[14:15], v[172:173], v[36:37]
	v_pk_fma_f32 v[34:35], v[12:13], v[170:171], v[34:35]
	s_waitcnt lgkmcnt(1)
	v_pk_fma_f32 v[38:39], v[30:31], v[196:197], v[38:39]
	v_pk_fma_f32 v[40:41], v[28:29], v[194:195], v[40:41]
	v_add_f32_e32 v32, v34, v35
	v_add_f32_e32 v34, v36, v37
	v_add_f32_e32 v35, v38, v39
	v_pk_fma_f32 v[36:37], v[2:3], v[44:45], 0 op_sel_hi:[1,1,0]
	v_pk_fma_f32 v[38:39], v[0:1], v[42:43], 0 op_sel_hi:[1,1,0]
	v_lshl_add_u32 v158, v75, 2, v50
	v_add_f32_e32 v32, v32, v34
	v_add_f32_e32 v34, v40, v41
	v_pk_fma_f32 v[36:37], v[6:7], v[164:165], v[36:37]
	v_pk_fma_f32 v[38:39], v[4:5], v[162:163], v[38:39]
	ds_read_b32 v33, v158 offset:1024
	ds_read_b64 v[170:171], v50 offset:20736
	v_add_f32_e32 v34, v34, v35
	v_pk_fma_f32 v[36:37], v[10:11], v[176:177], v[36:37]
	v_pk_fma_f32 v[38:39], v[8:9], v[174:175], v[38:39]
	v_add_f32_e32 v32, v32, v34
	v_pk_fma_f32 v[166:167], v[14:15], v[180:181], v[36:37]
	v_pk_fma_f32 v[168:169], v[12:13], v[178:179], v[38:39]
	ds_read_b128 v[36:39], v59 offset:896
	ds_read_b128 v[40:43], v59 offset:928
	ds_read_b128 v[44:47], v59 offset:960
	ds_read_b128 v[162:165], v59 offset:992
	v_mov_b32_e32 v34, v32
	s_nop 1
	v_permlane32_swap_b32_e32 v32, v34
	s_waitcnt lgkmcnt(3)
	v_pk_fma_f32 v[38:39], v[18:19], v[38:39], 0 op_sel_hi:[1,1,0]
	v_pk_fma_f32 v[36:37], v[16:17], v[36:37], 0 op_sel_hi:[1,1,0]
	v_add_f32_e32 v35, v32, v34
	s_waitcnt lgkmcnt(2)
	v_pk_fma_f32 v[38:39], v[22:23], v[42:43], v[38:39]
	v_pk_fma_f32 v[36:37], v[20:21], v[40:41], v[36:37]
	v_cndmask_b32_e64 v32, v33, v35, s[6:7]
	s_waitcnt lgkmcnt(1)
	v_pk_fma_f32 v[38:39], v[26:27], v[46:47], v[38:39]
	v_pk_fma_f32 v[36:37], v[24:25], v[44:45], v[36:37]
	v_mfma_f32_32x32x2_f32 v[0:15], v198, v32, v[0:15]
	s_waitcnt lgkmcnt(0)
	v_fma_f32 v38, v30, v164, v38
	v_fma_f32 v39, v31, v165, v39
	v_fma_f32 v36, v28, v162, v36
	v_fma_f32 v37, v29, v163, v37
	v_add_f32_e32 v34, v166, v167
	v_mfma_f32_32x32x2_f32 v[16:31], v199, v32, v[16:31]
	v_add_f32_e32 v32, v168, v169
	v_add_f32_e32 v32, v32, v34
	v_add_f32_e32 v34, v36, v37
	v_add_f32_e32 v36, v38, v39
	v_add_f32_e32 v34, v34, v36
	v_add_f32_e32 v32, v32, v34
	v_mov_b32_e32 v34, v32
	s_nop 1
	v_permlane32_swap_b32_e32 v32, v34
	s_and_saveexec_b64 s[28:29], s[6:7]
	s_cbranch_execz .LBB0_503
	s_add_i32 s39, s30, 39
	s_and_b64 s[34:35], s[8:9], exec
	s_cselect_b32 s34, s26, s39
	s_ashr_i32 s35, s34, 31
	s_waitcnt lgkmcnt(0)
	v_mul_f32_e32 v35, v35, v170
	v_mul_f32_e32 v33, v33, v171
	v_pk_add_f32 v[32:33], v[32:33], v[34:35]
	s_nop 0
	v_add_f32_e32 v34, v32, v33
	v_lshl_add_u64 v[32:33], v[66:67], 0, s[34:35]
	v_lshlrev_b64 v[32:33], 11, v[32:33]
	v_lshl_add_u64 v[32:33], v[68:69], 0, v[32:33]
	global_store_dword v[32:33], v34, off
